# MLA task epilogue: 16 row-per-lane dwordx2 stores paired into 8 dwordx4 stores via v_permlane32_swap
# speedup vs baseline: 1.0003x; 1.0003x over previous
.LBB0_310:
	s_or_b64 exec, exec, s[40:41]
	v_and_b32_e32 v67, 64, v210
	v_xor_b32_e32 v66, 32, v210
	v_add_u32_e32 v67, 64, v67
	v_cmp_lt_i32_e32 vcc, v66, v67
	s_nop 1
	v_cndmask_b32_e32 v66, v210, v66, vcc
	v_lshlrev_b32_e32 v66, 2, v66
	ds_bpermute_b32 v66, v66, v233
	v_cmp_lt_u32_e32 vcc, v226, v175
	s_and_saveexec_b64 s[4:5], vcc
	s_cbranch_execz .LBB0_312
	v_readlane_b32 s6, v254, 20
	v_lshlrev_b64 v[68:69], 11, v[0:1]
	v_readlane_b32 s7, v254, 21
	s_waitcnt lgkmcnt(0)
	v_add_f32_e32 v70, v233, v66
	v_lshlrev_b32_e32 v0, 11, v226
	v_lshl_add_u64 v[68:69], s[6:7], 0, v[68:69]
	v_div_scale_f32 v71, s[6:7], v70, v70, 1.0
	v_rcp_f32_e32 v72, v71
	v_lshl_add_u64 v[68:69], v[68:69], 0, v[0:1]
	v_lshl_add_u64 v[66:67], v[176:177], 1, v[68:69]
	v_lshlrev_b32_e32 v0, 1, v179
	v_lshl_add_u64 v[66:67], v[66:67], 0, v[0:1]
	v_fma_f32 v0, -v71, v72, 1.0
	v_fmac_f32_e32 v72, v0, v72
	v_div_scale_f32 v0, vcc, 1.0, v70, 1.0
	v_mul_f32_e32 v68, v0, v72
	v_fma_f32 v69, -v71, v68, v0
	v_fmac_f32_e32 v68, v69, v72
	v_fma_f32 v0, -v71, v68, v0
	v_div_fmas_f32 v0, v0, v72, v68
	v_div_fixup_f32 v0, v0, v70, 1.0
	v_and_b32_e32 v70, 32, v210
	v_lshrrev_b32_e32 v70, 2, v70
	v_mov_b32_e32 v71, 0
	v_lshl_add_u64 v[68:69], v[66:67], 0, v[70:71]
	v_pk_mul_f32 v[34:35], v[34:35], v[0:1] op_sel_hi:[1,0]
	v_pk_mul_f32 v[36:37], v[36:37], v[0:1] op_sel_hi:[1,0]
	v_pk_mul_f32 v[38:39], v[38:39], v[0:1] op_sel_hi:[1,0]
	v_pk_mul_f32 v[40:41], v[40:41], v[0:1] op_sel_hi:[1,0]
	v_cvt_pk_bf16_f32 v34, v34, v35
	v_cvt_pk_bf16_f32 v35, v36, v37
	v_cvt_pk_bf16_f32 v36, v38, v39
	v_cvt_pk_bf16_f32 v37, v40, v41
	s_nop 1
	v_permlane32_swap_b32_e32 v34, v36
	v_permlane32_swap_b32_e32 v35, v37
	global_store_dwordx4 v[68:69], v[34:37], off
	v_pk_mul_f32 v[42:43], v[42:43], v[0:1] op_sel_hi:[1,0]
	v_pk_mul_f32 v[44:45], v[44:45], v[0:1] op_sel_hi:[1,0]
	v_pk_mul_f32 v[46:47], v[46:47], v[0:1] op_sel_hi:[1,0]
	v_pk_mul_f32 v[48:49], v[48:49], v[0:1] op_sel_hi:[1,0]
	v_cvt_pk_bf16_f32 v42, v42, v43
	v_cvt_pk_bf16_f32 v43, v44, v45
	v_cvt_pk_bf16_f32 v44, v46, v47
	v_cvt_pk_bf16_f32 v45, v48, v49
	s_nop 1
	v_permlane32_swap_b32_e32 v42, v44
	v_permlane32_swap_b32_e32 v43, v45
	global_store_dwordx4 v[68:69], v[42:45], off offset:32
	v_pk_mul_f32 v[50:51], v[50:51], v[0:1] op_sel_hi:[1,0]
	v_pk_mul_f32 v[52:53], v[52:53], v[0:1] op_sel_hi:[1,0]
	v_pk_mul_f32 v[54:55], v[54:55], v[0:1] op_sel_hi:[1,0]
	v_pk_mul_f32 v[56:57], v[56:57], v[0:1] op_sel_hi:[1,0]
	v_cvt_pk_bf16_f32 v50, v50, v51
	v_cvt_pk_bf16_f32 v51, v52, v53
	v_cvt_pk_bf16_f32 v52, v54, v55
	v_cvt_pk_bf16_f32 v53, v56, v57
	s_nop 1
	v_permlane32_swap_b32_e32 v50, v52
	v_permlane32_swap_b32_e32 v51, v53
	global_store_dwordx4 v[68:69], v[50:53], off offset:64
	v_pk_mul_f32 v[58:59], v[58:59], v[0:1] op_sel_hi:[1,0]
	v_pk_mul_f32 v[60:61], v[60:61], v[0:1] op_sel_hi:[1,0]
	v_pk_mul_f32 v[62:63], v[62:63], v[0:1] op_sel_hi:[1,0]
	v_pk_mul_f32 v[64:65], v[64:65], v[0:1] op_sel_hi:[1,0]
	v_cvt_pk_bf16_f32 v58, v58, v59
	v_cvt_pk_bf16_f32 v59, v60, v61
	v_cvt_pk_bf16_f32 v60, v62, v63
	v_cvt_pk_bf16_f32 v61, v64, v65
	s_nop 1
	v_permlane32_swap_b32_e32 v58, v60
	v_permlane32_swap_b32_e32 v59, v61
	global_store_dwordx4 v[68:69], v[58:61], off offset:96
	v_pk_mul_f32 v[18:19], v[18:19], v[0:1] op_sel_hi:[1,0]
	v_pk_mul_f32 v[20:21], v[20:21], v[0:1] op_sel_hi:[1,0]
	v_pk_mul_f32 v[22:23], v[22:23], v[0:1] op_sel_hi:[1,0]
	v_pk_mul_f32 v[24:25], v[24:25], v[0:1] op_sel_hi:[1,0]
	v_cvt_pk_bf16_f32 v18, v18, v19
	v_cvt_pk_bf16_f32 v19, v20, v21
	v_cvt_pk_bf16_f32 v20, v22, v23
	v_cvt_pk_bf16_f32 v21, v24, v25
	s_nop 1
	v_permlane32_swap_b32_e32 v18, v20
	v_permlane32_swap_b32_e32 v19, v21
	global_store_dwordx4 v[68:69], v[18:21], off offset:128
	v_pk_mul_f32 v[26:27], v[26:27], v[0:1] op_sel_hi:[1,0]
	v_pk_mul_f32 v[28:29], v[28:29], v[0:1] op_sel_hi:[1,0]
	v_pk_mul_f32 v[30:31], v[30:31], v[0:1] op_sel_hi:[1,0]
	v_pk_mul_f32 v[32:33], v[32:33], v[0:1] op_sel_hi:[1,0]
	v_cvt_pk_bf16_f32 v26, v26, v27
	v_cvt_pk_bf16_f32 v27, v28, v29
	v_cvt_pk_bf16_f32 v28, v30, v31
	v_cvt_pk_bf16_f32 v29, v32, v33
	s_nop 1
	v_permlane32_swap_b32_e32 v26, v28
	v_permlane32_swap_b32_e32 v27, v29
	global_store_dwordx4 v[68:69], v[26:29], off offset:160
	v_pk_mul_f32 v[2:3], v[2:3], v[0:1] op_sel_hi:[1,0]
	v_pk_mul_f32 v[4:5], v[4:5], v[0:1] op_sel_hi:[1,0]
	v_pk_mul_f32 v[6:7], v[6:7], v[0:1] op_sel_hi:[1,0]
	v_pk_mul_f32 v[8:9], v[8:9], v[0:1] op_sel_hi:[1,0]
	v_cvt_pk_bf16_f32 v2, v2, v3
	v_cvt_pk_bf16_f32 v3, v4, v5
	v_cvt_pk_bf16_f32 v4, v6, v7
	v_cvt_pk_bf16_f32 v5, v8, v9
	s_nop 1
	v_permlane32_swap_b32_e32 v2, v4
	v_permlane32_swap_b32_e32 v3, v5
	global_store_dwordx4 v[68:69], v[2:5], off offset:192
	v_pk_mul_f32 v[10:11], v[10:11], v[0:1] op_sel_hi:[1,0]
	v_pk_mul_f32 v[12:13], v[12:13], v[0:1] op_sel_hi:[1,0]
	v_pk_mul_f32 v[14:15], v[14:15], v[0:1] op_sel_hi:[1,0]
	v_pk_mul_f32 v[16:17], v[16:17], v[0:1] op_sel_hi:[1,0]
	v_cvt_pk_bf16_f32 v10, v10, v11
	v_cvt_pk_bf16_f32 v11, v12, v13
	v_cvt_pk_bf16_f32 v12, v14, v15
	v_cvt_pk_bf16_f32 v13, v16, v17
	s_nop 1
	v_permlane32_swap_b32_e32 v10, v12
	v_permlane32_swap_b32_e32 v11, v13
	global_store_dwordx4 v[68:69], v[10:13], off offset:224
